# XCD-local seams: row phases own their XCD token rows; 6 seams skip L2 writeback + cross-XCD arrival when the runtime placement check passes (global fallback otherwise)
# speedup vs baseline: 1.0264x; 1.0195x over previous
.LBB0_2:
	s_load_dword s2, s[0:1], 0xe0
	s_load_dwordx2 s[90:91], s[0:1], 0xd0
	s_load_dwordx4 s[92:95], s[0:1], 0xc0
	v_cmp_gt_u32_e32 vcc, 16, v146
	s_waitcnt lgkmcnt(0)
	v_writelane_b32 v241, s2, 2
	s_and_saveexec_b64 s[2:3], vcc
	v_mov_b32_e32 v1, 0x100
	v_lshl_add_u32 v1, v146, 2, v1
	v_add_u32_e32 v1, 0x20c00, v1
	v_mov_b32_e32 v2, 0
	ds_write_b32 v1, v2
	s_or_b64 exec, exec, s[2:3]
	s_waitcnt lgkmcnt(0)
	s_barrier
	s_getreg_b32 s2, hwreg(HW_REG_XCC_ID, 0, 4)
	s_and_b32 s33, s2, 15
	v_cmp_eq_u32_e64 s[4:5], 0, v146
	s_mov_b64 s[2:3], exec
	s_nop 0
	v_writelane_b32 v241, s4, 3
	s_nop 1
	v_writelane_b32 v241, s5, 4
	s_and_b64 s[4:5], s[2:3], s[4:5]
	s_mov_b64 exec, s[4:5]
	s_cbranch_execz .LBB0_7
	s_mov_b64 s[4:5], exec
	v_mbcnt_lo_u32_b32 v1, s4, 0
	v_mbcnt_hi_u32_b32 v1, s5, v1
	v_cmp_eq_u32_e32 vcc, 0, v1
	s_and_b64 s[6:7], exec, vcc
	s_mov_b64 exec, s[6:7]
	s_cbranch_execz .LBB0_7
	s_lshl_b32 s6, s33, 8
	s_bcnt1_i32_b64 s4, s[4:5]
	v_mov_b32_e32 v1, s6
	v_mov_b32_e32 v2, s4
	global_atomic_add v1, v2, s[94:95] offset:1024
	s_and_b32 s4, s72, 7
	s_lshl_b32 s4, s4, 2
	s_addk_i32 s4, 0x6200
	v_mov_b32_e32 v1, s4
	s_lshl_b32 s4, 1, s33
	v_mov_b32_e32 v2, s4
	global_atomic_or v1, v2, s[94:95]

.LBB0_95:
	v_mov_b32_e32 v1, 0x6200
	global_load_dwordx4 v[2:5], v1, s[94:95] sc1
	global_load_dwordx4 v[6:9], v1, s[94:95] offset:16 sc1
	s_waitcnt vmcnt(0)
	v_or3_b32 v10, v2, v3, v4
	v_or3_b32 v10, v10, v5, v6
	v_or3_b32 v10, v10, v7, v8
	v_or_b32_e32 v10, v10, v9
	v_bcnt_u32_b32 v10, v10, 0
	v_bcnt_u32_b32 v11, v2, 0
	v_bcnt_u32_b32 v11, v3, v11
	v_bcnt_u32_b32 v11, v4, v11
	v_bcnt_u32_b32 v11, v5, v11
	v_bcnt_u32_b32 v11, v6, v11
	v_bcnt_u32_b32 v11, v7, v11
	v_bcnt_u32_b32 v11, v8, v11
	v_bcnt_u32_b32 v11, v9, v11
	v_cmp_eq_u32_e32 vcc, 8, v10
	s_nop 1
	v_cndmask_b32_e64 v10, 0, 1, vcc
	v_cmp_eq_u32_e32 vcc, 8, v11
	s_nop 1
	v_cndmask_b32_e32 v10, 0, v10, vcc
	v_mov_b32_e32 v11, 0x20d20
	ds_write_b32 v11, v10
	s_waitcnt lgkmcnt(0)
	s_cmp_lt_i32 s90, 2
	s_cselect_b64 s[2:3], -1, 0
	s_and_b64 s[2:3], s[2:3], s[4:5]
	s_andn2_b64 vcc, exec, s[2:3]
	s_cbranch_vccnz .LBB0_106
	v_lshl_add_u32 v1, s72, 9, v146
	s_movk_i32 s4, 0x9ff
	v_cmp_lt_i32_e32 vcc, s4, v1
	s_and_saveexec_b64 s[4:5], vcc
	s_xor_b64 s[4:5], exec, s[4:5]
	v_lshlrev_b32_e32 v64, 2, v146
	s_andn2_saveexec_b64 s[4:5], s[4:5]
	s_cbranch_execz .LBB0_102
	v_readlane_b32 s8, v241, 0
	s_add_u32 s6, s94, 0x300000
	v_readlane_b32 s9, v241, 1
	v_lshlrev_b32_e32 v64, 2, v146
	v_readlane_b32 s36, v241, 5
	s_addc_u32 s7, s95, 0
	s_lshl_b32 s10, s8, 9
	v_lshl_add_u32 v2, s72, 11, v64
	s_lshl_b32 s11, s8, 11
	s_mov_b64 s[8:9], 0
	s_mov_b32 s12, 0x48000
	s_mov_b32 s13, 0x5a000
	s_mov_b32 s14, 0x6c000
	s_mov_b32 s15, 0x7e000
	s_mov_b32 s16, 0x90000
	s_mov_b32 s17, 0xa2000
	s_mov_b32 s18, 0xb4000
	s_mov_b32 s19, 0xc6000
	s_mov_b32 s22, 0xd8000
	s_mov_b32 s23, 0xea000
	s_mov_b32 s24, 0xfc000
	s_mov_b32 s25, 0x10e000
	s_movk_i32 s26, 0x9ff
	v_readlane_b32 s42, v241, 11
	v_readlane_b32 s43, v241, 12
	v_readlane_b32 s37, v241, 6
	v_readlane_b32 s38, v241, 7
	v_readlane_b32 s39, v241, 8
	v_readlane_b32 s40, v241, 9
	v_readlane_b32 s41, v241, 10
	v_readlane_b32 s44, v241, 13
	v_readlane_b32 s45, v241, 14
	v_readlane_b32 s46, v241, 15
	v_readlane_b32 s47, v241, 16
	v_readlane_b32 s48, v241, 17
	v_readlane_b32 s49, v241, 18
	v_readlane_b32 s50, v241, 19
	v_readlane_b32 s51, v241, 20

.LBB0_102:
	s_or_b64 exec, exec, s[4:5]
	v_add_u32_e32 v62, 0x800, v64
	v_mov_b32_e32 v63, 0
	v_lshlrev_b64 v[6:7], 2, v[62:63]
	v_lshl_add_u64 v[66:67], s[0:1], 0, v[6:7]
	v_add_co_u32_e32 v10, vcc, 0x12000, v66
	v_readlane_b32 s4, v241, 5
	s_nop 0
	v_addc_co_u32_e32 v11, vcc, 0, v67, vcc
	v_add_co_u32_e32 v14, vcc, 0x24000, v66
	v_readlane_b32 s10, v241, 11
	s_nop 0
	v_addc_co_u32_e32 v15, vcc, 0, v67, vcc
	v_add_co_u32_e32 v18, vcc, 0x36000, v66
	v_readlane_b32 s11, v241, 12
	s_nop 0
	v_addc_co_u32_e32 v19, vcc, 0, v67, vcc
	v_add_co_u32_e32 v22, vcc, 0x48000, v66
	v_lshl_add_u64 v[2:3], s[10:11], 0, v[6:7]
	s_nop 0
	v_addc_co_u32_e32 v23, vcc, 0, v67, vcc
	v_add_co_u32_e32 v26, vcc, 0x5a000, v66
	global_load_dwordx4 v[2:5], v[2:3], off
	s_nop 0
	v_addc_co_u32_e32 v27, vcc, 0, v67, vcc
	v_add_co_u32_e32 v30, vcc, 0x6c000, v66
	v_mov_b32_e32 v65, v63
	s_nop 0
	v_addc_co_u32_e32 v31, vcc, 0, v67, vcc
	v_add_co_u32_e32 v32, vcc, 0x7e000, v66
	v_readlane_b32 s12, v241, 13
	s_nop 0
	v_addc_co_u32_e32 v33, vcc, 0, v67, vcc
	v_add_co_u32_e32 v38, vcc, 0x90000, v66
	v_readlane_b32 s13, v241, 14
	s_nop 0
	v_addc_co_u32_e32 v39, vcc, 0, v67, vcc
	v_add_co_u32_e32 v40, vcc, 0xa2000, v66
	global_load_dwordx4 v[6:9], v[66:67], off
	s_nop 0
	global_load_dwordx4 v[10:13], v[10:11], off
	v_addc_co_u32_e32 v41, vcc, 0, v67, vcc
	v_add_co_u32_e32 v46, vcc, 0xb4000, v66
	v_lshlrev_b64 v[64:65], 2, v[64:65]
	s_nop 0
	v_addc_co_u32_e32 v47, vcc, 0, v67, vcc
	v_add_co_u32_e32 v48, vcc, 0xc6000, v66
	s_mov_b32 s4, 0x12000
	s_nop 0
	v_addc_co_u32_e32 v49, vcc, 0, v67, vcc
	v_add_co_u32_e32 v54, vcc, 0xd8000, v66
	v_lshl_add_u64 v[74:75], s[12:13], 0, v[64:65]
	s_nop 0
	v_addc_co_u32_e32 v55, vcc, 0, v67, vcc
	v_add_co_u32_e32 v58, vcc, 0xea000, v66
	v_lshl_add_u64 v[78:79], s[10:11], 0, v[64:65]
	s_nop 0
	v_addc_co_u32_e32 v59, vcc, 0, v67, vcc
	v_add_co_u32_e32 v68, vcc, 0xfc000, v66
	v_lshl_add_u64 v[64:65], s[0:1], 0, v[64:65]
	s_nop 0
	v_addc_co_u32_e32 v69, vcc, 0, v67, vcc
	v_add_co_u32_e32 v70, vcc, 0x10e000, v66
	global_load_dwordx4 v[14:17], v[14:15], off
	s_nop 0
	global_load_dwordx4 v[18:21], v[18:19], off
	v_addc_co_u32_e32 v71, vcc, 0, v67, vcc
	v_add_co_u32_e32 v86, vcc, s4, v64
	s_mov_b32 s0, 0x24000
	s_nop 0
	v_addc_co_u32_e32 v87, vcc, 0, v65, vcc
	global_load_dwordx4 v[22:25], v[22:23], off
	s_nop 0
	global_load_dwordx4 v[26:29], v[26:27], off
	v_add_co_u32_e32 v90, vcc, s0, v64
	s_mov_b32 s1, 0x36000
	s_nop 0
	v_addc_co_u32_e32 v91, vcc, 0, v65, vcc
	global_load_dwordx4 v[34:37], v[30:31], off
	s_nop 0
	global_load_dwordx4 v[30:33], v[32:33], off
	v_add_co_u32_e32 v94, vcc, s1, v64
	s_mov_b32 s4, 0x48000
	s_nop 0
	v_addc_co_u32_e32 v95, vcc, 0, v65, vcc
	v_readlane_b32 s5, v241, 6
	global_load_dwordx4 v[42:45], v[38:39], off
	s_nop 0
	global_load_dwordx4 v[38:41], v[40:41], off
	v_add_co_u32_e32 v98, vcc, s4, v64
	s_mov_b32 s5, 0x5a000
	s_nop 0
	v_addc_co_u32_e32 v99, vcc, 0, v65, vcc
	v_readlane_b32 s6, v241, 7
	global_load_dwordx4 v[50:53], v[46:47], off
	s_nop 0
	global_load_dwordx4 v[46:49], v[48:49], off
	v_add_co_u32_e32 v102, vcc, s5, v64
	s_mov_b32 s6, 0x6c000
	s_nop 0
	v_addc_co_u32_e32 v103, vcc, 0, v65, vcc
	v_readlane_b32 s7, v241, 8
	global_load_dwordx4 v[54:57], v[54:55], off
	s_nop 0
	global_load_dwordx4 v[58:61], v[58:59], off
	v_add_co_u32_e32 v106, vcc, s6, v64
	s_mov_b32 s7, 0x7e000
	s_nop 0
	v_addc_co_u32_e32 v107, vcc, 0, v65, vcc
	v_readlane_b32 s8, v241, 9
	global_load_dwordx4 v[66:69], v[68:69], off
	s_nop 0
	global_load_dwordx4 v[70:73], v[70:71], off
	v_add_co_u32_e32 v110, vcc, s7, v64
	s_mov_b32 s8, 0x90000
	s_nop 0
	v_addc_co_u32_e32 v111, vcc, 0, v65, vcc
	v_readlane_b32 s9, v241, 10
	global_load_dwordx4 v[74:77], v[74:75], off
	v_add_co_u32_e32 v114, vcc, s8, v64
	global_load_dwordx4 v[78:81], v[78:79], off
	s_mov_b32 s9, 0xa2000
	v_addc_co_u32_e32 v115, vcc, 0, v65, vcc
	global_load_dwordx4 v[82:85], v[64:65], off
	s_nop 0
	global_load_dwordx4 v[86:89], v[86:87], off
	v_add_co_u32_e32 v118, vcc, s9, v64
	s_mov_b32 s10, 0xb4000
	s_nop 0
	v_addc_co_u32_e32 v119, vcc, 0, v65, vcc
	global_load_dwordx4 v[90:93], v[90:91], off
	s_nop 0
	global_load_dwordx4 v[94:97], v[94:95], off
	v_add_co_u32_e32 v122, vcc, s10, v64
	s_mov_b32 s11, 0xc6000
	s_nop 0
	v_addc_co_u32_e32 v123, vcc, 0, v65, vcc
	global_load_dwordx4 v[98:101], v[98:99], off
	s_nop 0
	global_load_dwordx4 v[102:105], v[102:103], off
	v_add_co_u32_e32 v126, vcc, s11, v64
	s_mov_b32 s12, 0xd8000
	s_nop 0
	v_addc_co_u32_e32 v127, vcc, 0, v65, vcc
	global_load_dwordx4 v[106:109], v[106:107], off
	s_nop 0
	global_load_dwordx4 v[110:113], v[110:111], off
	v_add_co_u32_e32 v130, vcc, s12, v64
	s_mov_b32 s13, 0xea000
	s_nop 0
	v_addc_co_u32_e32 v131, vcc, 0, v65, vcc
	v_readlane_b32 s14, v241, 15
	global_load_dwordx4 v[114:117], v[114:115], off
	s_nop 0
	global_load_dwordx4 v[118:121], v[118:119], off
	v_add_co_u32_e32 v134, vcc, s13, v64
	s_mov_b32 s14, 0xfc000
	s_nop 0
	v_addc_co_u32_e32 v135, vcc, 0, v65, vcc
	v_readlane_b32 s15, v241, 16
	global_load_dwordx4 v[122:125], v[122:123], off
	s_nop 0
	global_load_dwordx4 v[126:129], v[126:127], off
	v_add_co_u32_e32 v138, vcc, s14, v64
	s_mov_b32 s15, 0x10e000
	s_nop 0
	v_addc_co_u32_e32 v139, vcc, 0, v65, vcc
	global_load_dwordx4 v[130:133], v[130:131], off
	s_nop 0
	global_load_dwordx4 v[134:137], v[134:135], off
	v_add_co_u32_e32 v64, vcc, s15, v64
	global_load_dwordx4 v[138:141], v[138:139], off
	s_nop 0
	v_addc_co_u32_e32 v65, vcc, 0, v65, vcc
	global_load_dwordx4 v[142:145], v[64:65], off
	s_waitcnt vmcnt(33)
	v_pk_add_f32 v[4:5], v[4:5], v[8:9]
	v_pk_add_f32 v[2:3], v[2:3], v[6:7]
	s_waitcnt vmcnt(32)
	v_pk_add_f32 v[4:5], v[4:5], v[12:13]
	v_pk_add_f32 v[2:3], v[2:3], v[10:11]
	s_waitcnt vmcnt(31)
	v_pk_add_f32 v[4:5], v[4:5], v[16:17]
	v_pk_add_f32 v[2:3], v[2:3], v[14:15]
	s_waitcnt vmcnt(30)
	v_pk_add_f32 v[4:5], v[4:5], v[20:21]
	v_pk_add_f32 v[2:3], v[2:3], v[18:19]
	s_waitcnt vmcnt(29)
	v_pk_add_f32 v[4:5], v[4:5], v[24:25]
	v_pk_add_f32 v[2:3], v[2:3], v[22:23]
	s_waitcnt vmcnt(28)
	v_pk_add_f32 v[4:5], v[4:5], v[28:29]
	v_pk_add_f32 v[2:3], v[2:3], v[26:27]
	s_waitcnt vmcnt(27)
	v_pk_add_f32 v[4:5], v[4:5], v[36:37]
	v_pk_add_f32 v[2:3], v[2:3], v[34:35]
	s_waitcnt vmcnt(26)
	v_pk_add_f32 v[4:5], v[4:5], v[32:33]
	v_pk_add_f32 v[2:3], v[2:3], v[30:31]
	s_waitcnt vmcnt(25)
	v_pk_add_f32 v[4:5], v[4:5], v[44:45]
	v_pk_add_f32 v[2:3], v[2:3], v[42:43]
	s_waitcnt vmcnt(24)
	v_pk_add_f32 v[4:5], v[4:5], v[40:41]
	v_pk_add_f32 v[2:3], v[2:3], v[38:39]
	s_waitcnt vmcnt(23)
	v_pk_add_f32 v[4:5], v[4:5], v[52:53]
	v_pk_add_f32 v[2:3], v[2:3], v[50:51]
	s_waitcnt vmcnt(22)
	v_pk_add_f32 v[4:5], v[4:5], v[48:49]
	v_pk_add_f32 v[2:3], v[2:3], v[46:47]
	s_waitcnt vmcnt(21)
	v_pk_add_f32 v[4:5], v[4:5], v[56:57]
	v_pk_add_f32 v[2:3], v[2:3], v[54:55]
	s_waitcnt vmcnt(20)
	v_pk_add_f32 v[4:5], v[4:5], v[60:61]
	v_pk_add_f32 v[2:3], v[2:3], v[58:59]
	s_waitcnt vmcnt(19)
	v_pk_add_f32 v[4:5], v[4:5], v[68:69]
	v_pk_add_f32 v[2:3], v[2:3], v[66:67]
	s_waitcnt vmcnt(18)
	v_pk_add_f32 v[4:5], v[4:5], v[72:73]
	v_pk_add_f32 v[2:3], v[2:3], v[70:71]
	v_pk_add_f32 v[4:5], v[4:5], 1.0 op_sel_hi:[1,0]
	v_pk_add_f32 v[2:3], v[2:3], 1.0 op_sel_hi:[1,0]
	v_mov_b32_e32 v1, 0x100
	s_waitcnt vmcnt(17)
	v_pk_mul_f32 v[4:5], v[76:77], v[4:5]
	v_pk_mul_f32 v[2:3], v[74:75], v[2:3]
	v_lshl_add_u32 v1, v146, 4, v1
	ds_write_b128 v1, v[2:5] offset:8192
	s_waitcnt vmcnt(15)
	v_pk_add_f32 v[2:3], v[80:81], v[84:85]
	v_pk_add_f32 v[4:5], v[78:79], v[82:83]
	s_waitcnt vmcnt(14)
	v_pk_add_f32 v[2:3], v[2:3], v[88:89]
	v_pk_add_f32 v[4:5], v[4:5], v[86:87]
	s_waitcnt vmcnt(13)
	v_pk_add_f32 v[2:3], v[2:3], v[92:93]
	v_pk_add_f32 v[4:5], v[4:5], v[90:91]
	s_waitcnt vmcnt(12)
	v_pk_add_f32 v[2:3], v[2:3], v[96:97]
	v_pk_add_f32 v[4:5], v[4:5], v[94:95]
	s_waitcnt vmcnt(11)
	v_pk_add_f32 v[2:3], v[2:3], v[100:101]
	v_pk_add_f32 v[4:5], v[4:5], v[98:99]
	s_waitcnt vmcnt(10)
	v_pk_add_f32 v[2:3], v[2:3], v[104:105]
	v_pk_add_f32 v[4:5], v[4:5], v[102:103]
	s_cmpk_gt_i32 s96, 0x1fff
	s_waitcnt vmcnt(9)
	v_pk_add_f32 v[2:3], v[2:3], v[108:109]
	v_pk_add_f32 v[4:5], v[4:5], v[106:107]
	s_waitcnt vmcnt(8)
	v_pk_add_f32 v[2:3], v[2:3], v[112:113]
	v_pk_add_f32 v[4:5], v[4:5], v[110:111]
	v_readlane_b32 s16, v241, 17
	v_readlane_b32 s17, v241, 18
	v_readlane_b32 s18, v241, 19
	s_waitcnt vmcnt(7)
	v_pk_add_f32 v[2:3], v[2:3], v[116:117]
	v_pk_add_f32 v[4:5], v[4:5], v[114:115]
	s_waitcnt vmcnt(6)
	v_pk_add_f32 v[2:3], v[2:3], v[120:121]
	v_pk_add_f32 v[4:5], v[4:5], v[118:119]
	v_readlane_b32 s19, v241, 20
	s_waitcnt vmcnt(5)
	v_pk_add_f32 v[2:3], v[2:3], v[124:125]
	v_pk_add_f32 v[4:5], v[4:5], v[122:123]
	s_waitcnt vmcnt(4)
	v_pk_add_f32 v[2:3], v[2:3], v[128:129]
	v_pk_add_f32 v[4:5], v[4:5], v[126:127]
	s_waitcnt vmcnt(3)
	v_pk_add_f32 v[2:3], v[2:3], v[132:133]
	v_pk_add_f32 v[4:5], v[4:5], v[130:131]
	s_waitcnt vmcnt(2)
	v_pk_add_f32 v[2:3], v[2:3], v[136:137]
	v_pk_add_f32 v[4:5], v[4:5], v[134:135]
	s_waitcnt vmcnt(1)
	v_pk_add_f32 v[2:3], v[2:3], v[140:141]
	v_pk_add_f32 v[6:7], v[4:5], v[138:139]
	s_waitcnt vmcnt(0)
	v_pk_add_f32 v[4:5], v[2:3], v[144:145]
	v_pk_add_f32 v[2:3], v[6:7], v[142:143]
	ds_write_b128 v1, v[2:5] offset:16384
	s_waitcnt lgkmcnt(0)
	s_barrier
	s_cbranch_scc1 .LBB0_105
	v_mbcnt_lo_u32_b32 v1, -1, 0
	v_mbcnt_hi_u32_b32 v2, -1, v1
	v_and_b32_e32 v1, 64, v2
	v_add_u32_e32 v3, 64, v1
	v_xor_b32_e32 v1, 1, v2
	v_cmp_lt_i32_e32 vcc, v1, v3
	v_xor_b32_e32 v4, 2, v2
	s_lshr_b32 s98, s96, 8
	s_lshl_b32 s98, s98, 10
	s_and_b32 s99, s96, 0xff
	s_or_b32 s98, s98, s99
	s_mov_b32 s99, 0
	s_movk_i32 s100, 0x100
	s_mov_b32 s101, 0
	s_ashr_i32 s97, s96, 31
	v_cndmask_b32_e32 v1, v2, v1, vcc
	v_cmp_lt_i32_e32 vcc, v4, v3
	s_lshl_b64 s[0:1], s[98:99], 13
	v_readlane_b32 s4, v241, 5
	v_cndmask_b32_e32 v4, v2, v4, vcc
	v_lshlrev_b32_e32 v46, 2, v4
	v_xor_b32_e32 v4, 4, v2
	v_cmp_lt_i32_e32 vcc, v4, v3
	v_readlane_b32 s5, v241, 6
	s_add_u32 s0, s4, s0
	v_cndmask_b32_e32 v4, v2, v4, vcc
	v_lshlrev_b32_e32 v47, 2, v4
	v_xor_b32_e32 v4, 8, v2
	v_cmp_lt_i32_e32 vcc, v4, v3
	v_lshlrev_b32_e32 v62, 4, v147
	s_addc_u32 s1, s5, s1
	v_cndmask_b32_e32 v4, v2, v4, vcc
	v_lshlrev_b32_e32 v48, 2, v4
	v_xor_b32_e32 v4, 16, v2
	v_cmp_lt_i32_e32 vcc, v4, v3
	s_ashr_i32 s87, s86, 31
	s_lshl_b64 s[4:5], s[98:99], 12
	v_cndmask_b32_e32 v4, v2, v4, vcc
	v_lshlrev_b32_e32 v49, 2, v4
	v_xor_b32_e32 v4, 32, v2
	v_cmp_lt_i32_e32 vcc, v4, v3
	v_add_u32_e32 v51, 0x100, v62
	v_readlane_b32 s6, v241, 7
	v_cndmask_b32_e32 v2, v2, v4, vcc
	v_lshlrev_b32_e32 v50, 2, v2
	v_lshl_add_u64 v[2:3], s[0:1], 0, v[62:63]
	s_mov_b64 s[0:1], 0x1000
	v_lshl_add_u64 v[42:43], v[2:3], 0, s[0:1]
	s_lshl_b64 s[0:1], s[100:101], 13
	s_add_u32 s4, s94, s4
	v_lshlrev_b32_e32 v62, 3, v147
	s_addc_u32 s5, s95, s5
	v_lshl_add_u64 v[2:3], s[4:5], 0, v[62:63]
	s_mov_b64 s[4:5], 0xa400000
	v_lshlrev_b32_e32 v1, 2, v1
	v_lshl_add_u64 v[44:45], v[2:3], 0, s[4:5]
	s_lshl_b64 s[4:5], s[100:101], 12
	v_mov_b32_e32 v52, 0x358637bd
	s_mov_b32 s6, s96
	v_readlane_b32 s7, v241, 8
	v_readlane_b32 s8, v241, 9
	v_readlane_b32 s9, v241, 10
	v_readlane_b32 s10, v241, 11
	v_readlane_b32 s11, v241, 12
	v_readlane_b32 s12, v241, 13
	v_readlane_b32 s13, v241, 14
	v_readlane_b32 s14, v241, 15
	v_readlane_b32 s15, v241, 16
	v_readlane_b32 s16, v241, 17
	v_readlane_b32 s17, v241, 18
	v_readlane_b32 s18, v241, 19
	v_readlane_b32 s19, v241, 20

.LBB0_139:
	s_andn2_saveexec_b64 s[6:7], s[6:7]
	s_cbranch_execz .LBB0_159
	s_mov_b64 s[6:7], exec
	v_mov_b32_e32 v145, 0x20d20
	ds_read_b32 v145, v145
	s_waitcnt lgkmcnt(0)
	v_cmp_ne_u32_e32 vcc, 0, v145
	s_cbranch_vccnz .LBB0_156
	buffer_wbl2 sc1
	s_waitcnt lgkmcnt(0)
	s_waitcnt vmcnt(0)
	v_mbcnt_lo_u32_b32 v2, s6, 0
	v_mbcnt_hi_u32_b32 v2, s7, v2
	v_cmp_eq_u32_e32 vcc, 0, v2
	s_and_saveexec_b64 s[8:9], vcc
	s_cbranch_execz .LBB0_142
	s_bcnt1_i32_b64 s6, s[6:7]
	v_mov_b32_e32 v3, 0x3000
	v_mov_b32_e32 v4, s6
	global_atomic_add v3, v3, v4, s[94:95] offset:1024 sc0

.LBB0_333:
	s_cmp_lt_i32 s90, 5
	s_cselect_b64 s[2:3], -1, 0
	s_and_b64 s[0:1], s[2:3], s[0:1]
	s_andn2_b64 vcc, exec, s[0:1]
	s_cbranch_vccnz .LBB0_338
	v_lshlrev_b32_e32 v2, 4, v146
	v_mov_b32_e32 v3, 0
	v_lshl_add_u64 v[20:21], s[94:95], 0, v[2:3]
	v_add_co_u32_e32 v8, vcc, 0x304000, v20
	v_readlane_b32 s4, v241, 5
	s_nop 0
	v_addc_co_u32_e32 v9, vcc, 0, v21, vcc
	s_mov_b32 s2, 0x308000
	v_readlane_b32 s12, v241, 13
	v_readlane_b32 s13, v241, 14
	v_add_co_u32_e32 v12, vcc, s2, v20
	v_readlane_b32 s14, v241, 15
	v_readlane_b32 s15, v241, 16
	v_addc_co_u32_e32 v13, vcc, 0, v21, vcc
	v_lshl_add_u64 v[16:17], s[12:13], 0, v[2:3]
	s_movk_i32 s2, 0x2000
	v_add_co_u32_e32 v16, vcc, s2, v16
	s_nop 0
	global_load_dwordx4 v[4:7], v2, s[14:15]
	s_nop 0
	global_load_dwordx4 v[8:11], v[8:9], off
	s_nop 0
	global_load_dwordx4 v[12:15], v[12:13], off
	v_addc_co_u32_e32 v17, vcc, 0, v17, vcc
	global_load_dwordx4 v[16:19], v[16:17], off
	v_add_co_u32_e32 v20, vcc, 0x306000, v20
	s_cmpk_gt_i32 s96, 0x1fff
	s_nop 0
	v_addc_co_u32_e32 v21, vcc, 0, v21, vcc
	global_load_dwordx4 v[20:23], v[20:21], off
	v_add_u32_e32 v1, 0x100, v2
	v_readlane_b32 s5, v241, 6
	v_readlane_b32 s6, v241, 7
	v_readlane_b32 s7, v241, 8
	v_readlane_b32 s8, v241, 9
	v_readlane_b32 s9, v241, 10
	v_readlane_b32 s10, v241, 11
	v_readlane_b32 s11, v241, 12
	v_readlane_b32 s16, v241, 17
	v_readlane_b32 s17, v241, 18
	v_readlane_b32 s18, v241, 19
	v_readlane_b32 s19, v241, 20
	s_waitcnt vmcnt(0)
	v_pk_mul_f32 v[6:7], v[10:11], v[6:7]
	v_pk_mul_f32 v[4:5], v[8:9], v[4:5]
	v_pk_add_f32 v[8:9], v[14:15], 1.0 op_sel_hi:[1,0]
	v_pk_add_f32 v[12:13], v[12:13], 1.0 op_sel_hi:[1,0]
	v_pk_mul_f32 v[6:7], v[6:7], 0.5 op_sel_hi:[1,0]
	v_pk_mul_f32 v[4:5], v[4:5], 0.5 op_sel_hi:[1,0]
	v_pk_mul_f32 v[10:11], v[18:19], v[8:9]
	v_pk_mul_f32 v[8:9], v[16:17], v[12:13]
	ds_write_b128 v1, v[4:7]
	ds_write_b128 v1, v[8:11] offset:8192
	ds_write_b128 v1, v[20:23] offset:16384
	s_waitcnt lgkmcnt(0)
	s_barrier
	s_cbranch_scc1 .LBB0_337
	v_mbcnt_lo_u32_b32 v1, -1, 0
	v_mbcnt_hi_u32_b32 v2, -1, v1
	v_and_b32_e32 v1, 64, v2
	v_add_u32_e32 v4, 64, v1
	v_xor_b32_e32 v1, 1, v2
	v_cmp_lt_i32_e32 vcc, v1, v4
	v_xor_b32_e32 v5, 2, v2
	s_lshr_b32 s98, s96, 8
	s_lshl_b32 s98, s98, 10
	s_and_b32 s99, s96, 0xff
	s_or_b32 s98, s98, s99
	s_mov_b32 s99, 0
	s_movk_i32 s100, 0x100
	s_mov_b32 s101, 0
	s_ashr_i32 s97, s96, 31
	v_cndmask_b32_e32 v1, v2, v1, vcc
	v_cmp_lt_i32_e32 vcc, v5, v4
	s_lshl_b64 s[2:3], s[98:99], 12
	s_add_u32 s2, s94, s2
	v_cndmask_b32_e32 v5, v2, v5, vcc
	v_lshlrev_b32_e32 v64, 2, v5
	v_xor_b32_e32 v5, 4, v2
	v_cmp_lt_i32_e32 vcc, v5, v4
	s_addc_u32 s3, s95, s3
	v_readlane_b32 s36, v241, 5
	v_cndmask_b32_e32 v5, v2, v5, vcc
	v_lshlrev_b32_e32 v65, 2, v5
	v_xor_b32_e32 v5, 8, v2
	v_cmp_lt_i32_e32 vcc, v5, v4
	s_ashr_i32 s87, s86, 31
	v_readlane_b32 s37, v241, 6
	v_cndmask_b32_e32 v5, v2, v5, vcc
	v_lshlrev_b32_e32 v66, 2, v5
	v_xor_b32_e32 v5, 16, v2
	v_cmp_lt_i32_e32 vcc, v5, v4
	s_lshl_b64 s[4:5], s[98:99], 13
	s_mov_b64 s[8:9], s[36:37]
	v_cndmask_b32_e32 v5, v2, v5, vcc
	v_lshlrev_b32_e32 v67, 2, v5
	v_xor_b32_e32 v5, 32, v2
	v_cmp_lt_i32_e32 vcc, v5, v4
	v_lshlrev_b32_e32 v4, 4, v147
	v_readlane_b32 s44, v241, 13
	v_cndmask_b32_e32 v2, v2, v5, vcc
	v_lshlrev_b32_e32 v68, 2, v2
	v_lshlrev_b32_e32 v2, 3, v147
	v_lshl_add_u64 v[6:7], s[2:3], 0, v[2:3]
	s_mov_b64 s[2:3], 0x12400000
	v_lshl_add_u64 v[38:39], v[6:7], 0, s[2:3]
	s_lshl_b64 s[2:3], s[100:101], 12
	s_add_u32 s4, s8, s4
	v_mov_b32_e32 v5, v3
	s_addc_u32 s5, s9, s5
	v_readlane_b32 s45, v241, 14
	v_lshl_add_u64 v[2:3], s[4:5], 0, v[4:5]
	s_mov_b64 s[4:5], 0x1000
	v_lshlrev_b32_e32 v1, 2, v1
	v_add_u32_e32 v69, 0x100, v4
	v_readlane_b32 s45, v241, 59
	v_readlane_b32 s44, v241, 58
	v_lshl_add_u64 v[40:41], v[2:3], 0, s[4:5]
	s_lshl_b64 s[4:5], s[100:101], 13
	v_mov_b32_e32 v70, 0x358637bd
	s_brev_b32 s6, 32
	s_brev_b32 s7, 31
	s_mov_b32 s8, 0xf8001000
	s_mov_b32 s9, s96
	v_readlane_b32 s38, v241, 7
	v_readlane_b32 s39, v241, 8
	v_readlane_b32 s40, v241, 9
	v_readlane_b32 s41, v241, 10
	v_readlane_b32 s42, v241, 11
	v_readlane_b32 s43, v241, 12
	v_readlane_b32 s46, v241, 15
	v_readlane_b32 s47, v241, 16
	v_readlane_b32 s48, v241, 17
	v_readlane_b32 s49, v241, 18
	v_readlane_b32 s50, v241, 19
	v_readlane_b32 s51, v241, 20

.LBB0_737:
	s_andn2_saveexec_b64 s[6:7], s[6:7]
	s_cbranch_execz .LBB0_757
	s_mov_b64 s[6:7], exec
	v_mov_b32_e32 v145, 0x20d20
	ds_read_b32 v145, v145
	s_waitcnt lgkmcnt(0)
	v_cmp_ne_u32_e32 vcc, 0, v145
	s_cbranch_vccnz .LBB0_754
	buffer_wbl2 sc1
	s_waitcnt lgkmcnt(0)
	s_waitcnt vmcnt(0)
	v_mbcnt_lo_u32_b32 v1, s6, 0
	v_mbcnt_hi_u32_b32 v1, s7, v1
	v_cmp_eq_u32_e32 vcc, 0, v1
	s_and_saveexec_b64 s[8:9], vcc
	s_cbranch_execz .LBB0_740
	s_bcnt1_i32_b64 s6, s[6:7]
	v_mov_b32_e32 v2, 0x3000
	v_mov_b32_e32 v3, s6
	global_atomic_add v2, v2, v3, s[94:95] offset:1024 sc0

.LBB0_758:
	s_cmp_lt_i32 s90, 9
	s_cselect_b64 s[2:3], -1, 0
	s_and_b64 s[2:3], s[2:3], s[0:1]
	s_andn2_b64 vcc, exec, s[2:3]
	s_cbranch_vccnz .LBB0_763
	v_lshlrev_b32_e32 v0, 4, v146
	v_mov_b32_e32 v1, 0
	v_lshl_add_u64 v[18:19], s[94:95], 0, v[0:1]
	v_add_co_u32_e32 v2, vcc, 0x30a000, v18
	v_lshl_add_u64 v[6:7], s[66:67], 0, v[0:1]
	s_waitcnt lgkmcnt(0)
	v_addc_co_u32_e32 v3, vcc, 0, v19, vcc
	v_add_co_u32_e32 v6, vcc, 0x2000, v6
	v_lshl_add_u64 v[14:15], s[64:65], 0, v[0:1]
	s_nop 0
	v_addc_co_u32_e32 v7, vcc, 0, v7, vcc
	v_add_co_u32_e32 v10, vcc, 0x30e000, v18
	global_load_dwordx4 v[2:5], v[2:3], off
	s_nop 0
	v_addc_co_u32_e32 v11, vcc, 0, v19, vcc
	global_load_dwordx4 v[6:9], v[6:7], off
	v_add_co_u32_e32 v14, vcc, 0x4000, v14
	global_load_dwordx4 v[10:13], v[10:11], off
	s_nop 0
	v_addc_co_u32_e32 v15, vcc, 0, v15, vcc
	global_load_dwordx4 v[14:17], v[14:15], off
	v_add_co_u32_e32 v18, vcc, 0x30c000, v18
	v_add_u32_e32 v0, 0x100, v0
	s_nop 0
	v_addc_co_u32_e32 v19, vcc, 0, v19, vcc
	global_load_dwordx4 v[18:21], v[18:19], off
	s_cmpk_gt_i32 s96, 0x1fff
	s_waitcnt vmcnt(0)
	v_pk_mul_f32 v[4:5], v[4:5], v[8:9]
	v_pk_mul_f32 v[2:3], v[2:3], v[6:7]
	ds_write_b128 v0, v[2:5]
	v_pk_add_f32 v[2:3], v[12:13], 1.0 op_sel_hi:[1,0]
	v_pk_add_f32 v[6:7], v[10:11], 1.0 op_sel_hi:[1,0]
	v_pk_mul_f32 v[4:5], v[16:17], v[2:3]
	v_pk_mul_f32 v[2:3], v[14:15], v[6:7]
	ds_write_b128 v0, v[2:5] offset:8192
	ds_write_b128 v0, v[18:21] offset:16384
	s_waitcnt lgkmcnt(0)
	s_barrier
	s_cbranch_scc1 .LBB0_762
	v_mbcnt_lo_u32_b32 v0, -1, 0
	v_mbcnt_hi_u32_b32 v0, -1, v0
	v_and_b32_e32 v2, 64, v0
	v_add_u32_e32 v2, 64, v2
	v_xor_b32_e32 v3, 1, v0
	v_cmp_lt_i32_e32 vcc, v3, v2
	s_lshr_b32 s98, s96, 8
	s_lshl_b32 s98, s98, 10
	s_and_b32 s99, s96, 0xff
	s_or_b32 s98, s98, s99
	s_mov_b32 s99, 0
	s_movk_i32 s100, 0x100
	s_mov_b32 s101, 0
	s_ashr_i32 s97, s96, 31
	s_lshl_b64 s[0:1], s[98:99], 12
	v_cndmask_b32_e32 v3, v0, v3, vcc
	v_lshlrev_b32_e32 v28, 2, v3
	v_xor_b32_e32 v3, 2, v0
	v_cmp_lt_i32_e32 vcc, v3, v2
	s_add_u32 s0, s94, s0
	s_addc_u32 s1, s95, s1
	v_cndmask_b32_e32 v3, v0, v3, vcc
	v_lshlrev_b32_e32 v29, 2, v3
	v_xor_b32_e32 v3, 4, v0
	v_cmp_lt_i32_e32 vcc, v3, v2
	s_ashr_i32 s87, s86, 31
	s_lshl_b64 s[4:5], s[100:101], 12
	v_cndmask_b32_e32 v3, v0, v3, vcc
	v_lshlrev_b32_e32 v30, 2, v3
	v_xor_b32_e32 v3, 8, v0
	v_cmp_lt_i32_e32 vcc, v3, v2
	v_mov_b32_e32 v35, 0x358637bd
	s_brev_b32 s6, 31
	v_cndmask_b32_e32 v3, v0, v3, vcc
	v_lshlrev_b32_e32 v31, 2, v3
	v_xor_b32_e32 v3, 16, v0
	v_cmp_lt_i32_e32 vcc, v3, v2
	s_mov_b32 s7, 0xf8001000
	s_mov_b32 s8, s96
	v_cndmask_b32_e32 v3, v0, v3, vcc
	v_lshlrev_b32_e32 v32, 2, v3
	v_xor_b32_e32 v3, 32, v0
	v_cmp_lt_i32_e32 vcc, v3, v2
	s_nop 1
	v_cndmask_b32_e32 v0, v0, v3, vcc
	v_lshlrev_b32_e32 v33, 2, v0
	v_mov_b32_e32 v0, 0x100
	v_lshl_add_u32 v34, v147, 4, v0
	v_lshlrev_b32_e32 v0, 3, v147
	v_lshl_add_u64 v[0:1], s[0:1], 0, v[0:1]
	s_mov_b64 s[0:1], 0x12400000
	v_lshl_add_u64 v[4:5], v[0:1], 0, s[0:1]

.LBB0_971:
	s_cmp_lt_i32 s90, 12
	s_cselect_b64 s[2:3], -1, 0
	s_and_b64 s[0:1], s[2:3], s[0:1]
	s_andn2_b64 vcc, exec, s[0:1]
	s_cbranch_vccnz .LBB0_976
	v_lshlrev_b32_e32 v34, 4, v146
	v_mov_b32_e32 v35, 0
	v_lshl_add_u64 v[0:1], s[94:95], 0, v[34:35]
	v_add_co_u32_e32 v0, vcc, 0x310000, v0
	s_waitcnt lgkmcnt(0)
	v_lshl_add_u64 v[4:5], s[66:67], 0, v[34:35]
	v_addc_co_u32_e32 v1, vcc, 0, v1, vcc
	v_add_co_u32_e32 v4, vcc, 0x4000, v4
	global_load_dwordx4 v[0:3], v[0:1], off
	s_nop 0
	v_addc_co_u32_e32 v5, vcc, 0, v5, vcc
	global_load_dwordx4 v[4:7], v[4:5], off
	s_cmpk_gt_i32 s96, 0x1fff
	v_add_u32_e32 v8, 0x100, v34
	s_waitcnt vmcnt(0)
	v_pk_mul_f32 v[2:3], v[2:3], v[6:7]
	v_pk_mul_f32 v[0:1], v[0:1], v[4:5]
	v_pk_mul_f32 v[2:3], v[2:3], 0.5 op_sel_hi:[1,0]
	v_pk_mul_f32 v[0:1], v[0:1], 0.5 op_sel_hi:[1,0]
	ds_write_b128 v8, v[0:3]
	s_waitcnt lgkmcnt(0)
	s_barrier
	s_cbranch_scc1 .LBB0_975
	v_mbcnt_lo_u32_b32 v0, -1, 0
	v_mbcnt_hi_u32_b32 v0, -1, v0
	v_and_b32_e32 v1, 64, v0
	v_add_u32_e32 v1, 64, v1
	v_xor_b32_e32 v2, 1, v0
	v_cmp_lt_i32_e32 vcc, v2, v1
	v_lshlrev_b32_e32 v36, 4, v147
	v_add_u32_e32 v28, 0x100, v36
	v_cndmask_b32_e32 v2, v0, v2, vcc
	v_lshlrev_b32_e32 v54, 2, v2
	v_xor_b32_e32 v2, 2, v0
	v_cmp_lt_i32_e32 vcc, v2, v1
	s_lshr_b32 s98, s96, 8
	s_lshl_b32 s98, s98, 10
	s_and_b32 s99, s96, 0xff
	s_or_b32 s98, s98, s99
	s_mov_b32 s99, 0
	s_movk_i32 s100, 0x100
	s_mov_b32 s101, 0
	s_ashr_i32 s97, s96, 31
	s_lshl_b64 s[0:1], s[98:99], 12
	v_cndmask_b32_e32 v2, v0, v2, vcc
	v_lshlrev_b32_e32 v55, 2, v2
	v_xor_b32_e32 v2, 4, v0
	v_cmp_lt_i32_e32 vcc, v2, v1
	s_add_u32 s0, s94, s0
	v_lshlrev_b32_e32 v34, 3, v147
	v_cndmask_b32_e32 v2, v0, v2, vcc
	v_lshlrev_b32_e32 v56, 2, v2
	v_xor_b32_e32 v2, 8, v0
	v_cmp_lt_i32_e32 vcc, v2, v1
	s_addc_u32 s1, s95, s1
	v_lshl_add_u64 v[32:33], s[0:1], 0, v[34:35]
	v_cndmask_b32_e32 v2, v0, v2, vcc
	v_lshlrev_b32_e32 v57, 2, v2
	v_xor_b32_e32 v2, 16, v0
	v_cmp_lt_i32_e32 vcc, v2, v1
	s_mov_b64 s[0:1], 0x12400000
	s_ashr_i32 s87, s86, 31
	v_cndmask_b32_e32 v2, v0, v2, vcc
	v_lshlrev_b32_e32 v58, 2, v2
	v_xor_b32_e32 v2, 32, v0
	v_cmp_lt_i32_e32 vcc, v2, v1
	v_lshl_add_u64 v[32:33], v[32:33], 0, s[0:1]
	s_lshl_b64 s[0:1], s[100:101], 12
	v_cndmask_b32_e32 v0, v0, v2, vcc
	v_lshlrev_b32_e32 v59, 2, v0
	ds_read_b128 v[0:3], v28
	ds_read_b128 v[4:7], v28 offset:1024
	ds_read_b128 v[8:11], v28 offset:2048
	ds_read_b128 v[12:15], v28 offset:3072
	ds_read_b128 v[16:19], v28 offset:4096
	ds_read_b128 v[20:23], v28 offset:5120
	ds_read_b128 v[24:27], v28 offset:6144
	ds_read_b128 v[28:31], v28 offset:7168
	s_lshl_b64 s[2:3], s[98:99], 13
	s_add_u32 s2, s92, s2
	v_mov_b32_e32 v37, v35
	s_addc_u32 s3, s93, s3
	v_lshl_add_u64 v[34:35], s[2:3], 0, v[36:37]
	s_mov_b64 s[2:3], 0x1000
	v_lshl_add_u64 v[34:35], v[34:35], 0, s[2:3]
	s_lshl_b64 s[2:3], s[100:101], 13
	v_mov_b32_e32 v60, 0x358637bd
